# code placement: f32 and bf16 K-loop heads padded back to the baseline byte phases (52 / 48 mod 64)
# baseline (speedup 1.0000x reference)
;     ...
;         const bool has_next = S.next(ui + 1, nxt);
;         const char* nA = has_next ? nxt.A : cA; const char* nB = has_next ? nxt.B : cB;
;         for (int t = 0; t < nt; t += 2) {
;             const bool last = (t == nt - 2);
;             const char* a1 = cA + (size_t)(t + 1) * kstep;
;             const char* a2 = last ? nA : cA + (size_t)(t + 2) * kstep; const char* b2 = last ? nB : cB + (size_t)(t + 2) * kstep;
.LBB0_317:
	s_mov_b64 s[54:55], s[68:69]
	v_mov_b32_e32 v189, v128
	s_xor_b64 s[66:67], s[64:65], -1
	v_mov_b32_e32 v128, s55
	s_mov_b64 s[36:37], s[38:39]
	s_and_b64 s[0:1], s[64:65], exec
	v_cndmask_b32_e64 v132, v161, v128, s[64:65]
	v_mov_b32_e32 v128, s54
	s_mov_b64 s[6:7], s[56:57]
	s_mov_b64 s[14:15], s[58:59]
	s_mov_b32 s26, s19
	s_cselect_b32 s13, s37, s3
	s_cselect_b32 s56, s36, s2
	v_cndmask_b32_e64 v133, v160, v128, s[64:65]
	s_mov_b32 s38, 0
	s_mov_b64 s[0:1], 0x100
	v_mov_b64_e32 v[128:129], v[172:173]
	v_mov_b64_e32 v[130:131], v[170:171]
	s_nop 0
	s_nop 0
	s_nop 0
	s_nop 0
	s_nop 0
	s_nop 0
	s_nop 0
	s_nop 0
	s_nop 0
